# conv: next channel's x/v rows and KF/KB filters touched (one dword per lane) after the image barrier so the next channel's serialized prologue loads hit L2
# speedup vs baseline: 1.0109x; 1.0042x over previous
; DI void hy_conv_phase(int wvs, char* smem, bf16_t* X1T, const bf16_t* __restrict__ VT, const float* __restrict__ cw, const float* __restrict__ cb,
;                       const bf16_t* __restrict__ KF, const bf16_t* __restrict__ KB, bool dostore = true) {
;     ...
;   for (int c = blockIdx.x; c < 2048; c += gridDim.x) {
;     const float xa = cw[2048 + c], xb = cw[6144 + 2048 + c], xc = cw[12288 + 2048 + c], xbias = cb[2048 + c];
;     const float va = cw[4096 + c], vb = cw[6144 + 4096 + c], vc = cw[12288 + 4096 + c], vbias = cb[4096 + c];
;     const bf16_t* xrow = X1T + (size_t)c * 8 * SEQ;
;     const bf16_t* vrow = VT + (size_t)c * 8 * SEQ;
;     __syncthreads();
; #pragma unroll 2
;     for (int i = 0; i < 8; ++i) {
;       const int e = tid + NT * i, b = e >> 9, t8 = (e & 511) * 8;
;       const bf16_t* xp_ = xrow + b * SEQ + t8;
;       const bf16_t* vp_ = vrow + b * SEQ + t8;
;       const u32x4 xv = *(const u32x4*)xp_, vv = *(const u32x4*)vp_;
;       float fx[10], fv[10];
;       fx[0] = t8 > 0 ? bf2f(xp_[-1]) : 0.f; fv[0] = t8 > 0 ? bf2f(vp_[-1]) : 0.f;
;       fx[9] = t8 + 8 < SEQ ? bf2f(xp_[8]) : 0.f; fv[9] = t8 + 8 < SEQ ? bf2f(vp_[8]) : 0.f;
;       unpack8(xv, fx + 1); unpack8(vv, fv + 1);
;       float u[8];
; #pragma unroll
;       for (int j = 0; j < 8; ++j)
;         u[j] = (fx[j] * xa + fx[j + 1] * xb + fx[j + 2] * xc + xbias) * (fv[j] * va + fv[j + 1] * vb + fv[j + 2] * vc + vbias);
;       *(bf16x8*)(Uimg + ((t8 >> 6) * 8 + b) * 72 + (t8 & 63)) = pack8f(u);
;     }
;     {
;       const int t8 = tid * 8;
;       const u32x4 vf = *(const u32x4*)(KF + (size_t)c * SEQ + t8);
;       const u32x4 vb2 = *(const u32x4*)(KB + (size_t)c * SEQ + t8);
; #pragma unroll
;       for (int j = 0; j < 8; ++j) {
;         const bf16_t hfv = (bf16_t)((j & 1) ? (vf[j >> 1] >> 16) : (vf[j >> 1] & 0xffffu));
;         const bf16_t hbv = (bf16_t)((j & 1) ? (vb2[j >> 1] >> 16) : (vb2[j >> 1] & 0xffffu));
;         const int tt = t8 + j;
;         const int y = 4095 - tt;
;         R0[y] = hfv;
;         if (y >= 1) R1[y - 1] = hfv;
;         if (tt >= 1) { const int y2 = 4095 + tt; R0[y2] = hbv; R1[y2 - 1] = hbv; }
;       }
;       if (tid == 0) { R0[8191] = 0; R1[8190] = 0; R1[8191] = 0; }
;     }
;     __syncthreads();
;     const int b = n & 7, t1a = 8 * w + (n >> 3);
;     const bf16_t* Rb = (n & 1) ? R0 : (R1 - 1);
.LBB0_1208:
	s_or_b64 exec, exec, s[22:23]
	v_mov_b32_e32 v15, 0
	v_mov_b32_e32 v14, v15
	v_mov_b32_e32 v13, v15
	v_mov_b32_e32 v12, v15
	v_mov_b32_e32 v11, v15
	v_mov_b32_e32 v10, v15
	v_mov_b32_e32 v9, v15
	v_mov_b32_e32 v8, v15
	v_mov_b32_e32 v7, v15
	v_mov_b32_e32 v6, v15
	v_mov_b32_e32 v5, v15
	v_mov_b32_e32 v4, v15
	v_mov_b32_e32 v3, v15
	v_mov_b32_e32 v2, v15
	v_mov_b32_e32 v1, v15
	v_mov_b32_e32 v0, v15
	v_mov_b32_e32 v31, v15
	v_mov_b32_e32 v30, v15
	v_mov_b32_e32 v29, v15
	v_mov_b32_e32 v28, v15
	v_mov_b32_e32 v27, v15
	v_mov_b32_e32 v26, v15
	v_mov_b32_e32 v25, v15
	v_mov_b32_e32 v24, v15
	v_mov_b32_e32 v23, v15
	v_mov_b32_e32 v22, v15
	v_mov_b32_e32 v21, v15
	v_mov_b32_e32 v20, v15
	v_mov_b32_e32 v19, v15
	v_mov_b32_e32 v18, v15
	v_mov_b32_e32 v17, v15
	v_mov_b32_e32 v16, v15
	v_mov_b32_e32 v47, v15
	v_mov_b32_e32 v46, v15
	v_mov_b32_e32 v45, v15
	v_mov_b32_e32 v44, v15
	v_mov_b32_e32 v43, v15
	v_mov_b32_e32 v42, v15
	v_mov_b32_e32 v41, v15
	v_mov_b32_e32 v40, v15
	v_mov_b32_e32 v39, v15
	v_mov_b32_e32 v38, v15
	v_mov_b32_e32 v37, v15
	v_mov_b32_e32 v36, v15
	v_mov_b32_e32 v35, v15
	v_mov_b32_e32 v34, v15
	v_mov_b32_e32 v33, v15
	v_mov_b32_e32 v32, v15
	v_mov_b32_e32 v63, v15
	v_mov_b32_e32 v62, v15
	v_mov_b32_e32 v61, v15
	v_mov_b32_e32 v60, v15
	v_mov_b32_e32 v59, v15
	v_mov_b32_e32 v58, v15
	v_mov_b32_e32 v57, v15
	v_mov_b32_e32 v56, v15
	v_mov_b32_e32 v55, v15
	v_mov_b32_e32 v54, v15
	v_mov_b32_e32 v53, v15
	v_mov_b32_e32 v52, v15
	v_mov_b32_e32 v51, v15
	v_mov_b32_e32 v50, v15
	v_mov_b32_e32 v49, v15
	v_mov_b32_e32 v48, v15
	s_waitcnt lgkmcnt(0)
	s_barrier
	v_readlane_b32 s6, v251, 20
	s_add_i32 s6, s82, s6
	s_cmpk_lt_i32 s6, 0x800
	s_cbranch_scc0 .Lcv_nopf
	v_mbcnt_lo_u32_b32 v248, -1, 0
	v_mbcnt_hi_u32_b32 v248, -1, v248
	v_or_b32_e32 v248, s92, v248
	v_mul_u32_u24_e32 v248, 0x70, v248
	v_mov_b32_e32 v249, 0
	s_lshl_b32 s6, s6, 13
	s_mov_b32 s7, 0
	v_lshl_add_u64 v[246:247], v[124:125], 0, s[6:7]
	v_lshl_add_u64 v[244:245], v[126:127], 0, s[6:7]
	global_load_dword v250, v[246:247], off
	global_load_dword v250, v[244:245], off
	s_lshl_b32 s6, s6, 3
	v_lshl_add_u64 v[246:247], v[120:121], 0, v[248:249]
	v_lshl_add_u64 v[244:245], v[122:123], 0, v[248:249]
	v_lshl_add_u64 v[246:247], v[246:247], 0, s[6:7]
	v_lshl_add_u64 v[244:245], v[244:245], 0, s[6:7]
	global_load_dword v250, v[246:247], off
	global_load_dword v250, v[244:245], off
.Lcv_nopf:
	s_and_saveexec_b64 s[86:87], s[44:45]
	s_cbranch_execz .LBB0_1166
	v_add_u32_e32 v0, 0x205e, v138
	v_add_u32_e32 v1, 0x2066, v138
	v_add_u32_e32 v2, 0x203e, v138
	v_add_u32_e32 v3, 0x2046, v138
	ds_read2_b32 v[64:65], v0 offset1:1
	ds_read2_b32 v[66:67], v1 offset1:1
	ds_read2_b32 v[68:69], v2 offset1:1
	ds_read2_b32 v[70:71], v3 offset1:1
	v_mov_b32_e32 v0, 0
	s_mov_b64 s[88:89], 0
	v_mov_b32_e32 v175, v174
	v_mov_b32_e32 v187, v173
	v_mov_b32_e32 v188, v172
	v_mov_b32_e32 v189, v171
	v_mov_b32_e32 v1, v0
	v_mov_b32_e32 v2, v0
	v_mov_b32_e32 v3, v0
	v_mov_b32_e32 v4, v0
	v_mov_b32_e32 v5, v0
	v_mov_b32_e32 v6, v0
	v_mov_b32_e32 v7, v0
	v_mov_b32_e32 v8, v0
	v_mov_b32_e32 v9, v0
	v_mov_b32_e32 v10, v0
	v_mov_b32_e32 v11, v0
	v_mov_b32_e32 v12, v0
	v_mov_b32_e32 v13, v0
	v_mov_b32_e32 v14, v0
	v_mov_b32_e32 v15, v0
	v_mov_b32_e32 v16, v0
	v_mov_b32_e32 v17, v0
	v_mov_b32_e32 v18, v0
	v_mov_b32_e32 v19, v0
	v_mov_b32_e32 v20, v0
	v_mov_b32_e32 v21, v0
	v_mov_b32_e32 v22, v0
	v_mov_b32_e32 v23, v0
	v_mov_b32_e32 v24, v0
	v_mov_b32_e32 v25, v0
	v_mov_b32_e32 v26, v0
	v_mov_b32_e32 v27, v0
	v_mov_b32_e32 v28, v0
	v_mov_b32_e32 v29, v0
	v_mov_b32_e32 v30, v0
	v_mov_b32_e32 v31, v0
	v_mov_b32_e32 v32, v0
	v_mov_b32_e32 v33, v0
	v_mov_b32_e32 v34, v0
	v_mov_b32_e32 v35, v0
	v_mov_b32_e32 v36, v0
	v_mov_b32_e32 v37, v0
	v_mov_b32_e32 v38, v0
	v_mov_b32_e32 v39, v0
	v_mov_b32_e32 v40, v0
	v_mov_b32_e32 v41, v0
	v_mov_b32_e32 v42, v0
	v_mov_b32_e32 v43, v0
	v_mov_b32_e32 v44, v0
	v_mov_b32_e32 v45, v0
	v_mov_b32_e32 v46, v0
	v_mov_b32_e32 v47, v0
	v_mov_b32_e32 v48, v0
	v_mov_b32_e32 v49, v0
	v_mov_b32_e32 v50, v0
	v_mov_b32_e32 v51, v0
	v_mov_b32_e32 v52, v0
	v_mov_b32_e32 v53, v0
	v_mov_b32_e32 v54, v0
	v_mov_b32_e32 v55, v0
	v_mov_b32_e32 v56, v0
	v_mov_b32_e32 v57, v0
	v_mov_b32_e32 v58, v0
	v_mov_b32_e32 v59, v0
	v_mov_b32_e32 v60, v0
	v_mov_b32_e32 v61, v0
	v_mov_b32_e32 v62, v0
	v_mov_b32_e32 v63, v0
	s_branch .LBB0_1211
